# adds SGPR-base LDS-DMA addressing in the GEMM main loop (no 64-bit VALU address adds) and inline-zero SrcC instead of the VALU zero-init in the differential-attention QK block, on top of the hand-writ
# speedup vs baseline: 1.0086x; 1.0043x over previous
; #define PG8_STAGE(bufoff, gbase, voff) do { _Pragma("unroll") for (int _i = 0; _i < 2; ++_i) \
;         __builtin_amdgcn_global_load_lds((const unsigned*)((const char*)(gbase) + (voff)[_i]), (LAS unsigned*)(lds + (bufoff) + ldsw + _i * 8192), 16, 0, 0); } while (0)
; #define PG8_LDA(dst, b, h) do { _Pragma("unroll") for (int m = 0; m < 4; ++m) _Pragma("unroll") for (int k = 0; k < 2; ++k) dst[m][k] = *(const LAS bf16x8*)(lds + PG8_SA(b, h) + aoff + m * 2048 + k * 1024); } while (0)
; #define PG8_LDB(dst, b, h) do { _Pragma("unroll") for (int n = 0; n < 2; ++n) _Pragma("unroll") for (int k = 0; k < 2; ++k) dst[n][k] = *(const LAS bf16x8*)(lds + PG8_SB(b, h) + boff + n * 2048 + k * 1024); } while (0)
; #define PG8_MMA(ai, bj, At, Bt) do { __builtin_amdgcn_s_setprio(1); _Pragma("unroll") for (int m = 0; m < 4; ++m) _Pragma("unroll") for (int n = 0; n < 2; ++n) _Pragma("unroll") for (int k = 0; k < 2; ++k) \
;         acc[ai][bj][m][n] = __builtin_amdgcn_mfma_f32_16x16x32_bf16(Bt[n][k], At[m][k], acc[ai][bj][m][n], 0, 0, 0); __builtin_amdgcn_s_setprio(0); } while (0)
; #define PG8_WAIT_V(n) asm volatile("s_waitcnt vmcnt(" #n ")" ::: "memory")
; #define PG8_WAIT_L(n) asm volatile("s_waitcnt lgkmcnt(" #n ")" ::: "memory")
; #define PG8_BAR __builtin_amdgcn_s_barrier()
; #define PG8_SCHED __builtin_amdgcn_sched_barrier(0)
; __device__ __forceinline__ void gemm_phase(LAS unsigned char* lds, const Gemm g, const StaticOrder& S, const Epi& E) {
;     ...
;             PG8_LDB(B0, 0, 0); PG8_LDB(B1, 0, 1); PG8_SCHED; PG8_LDA(At, 0, 0); PG8_STAGE(PG8_SA(1, 1), a1 + hstepA, voffA);
;             PG8_WAIT_V(8); PG8_WAIT_L(0); PG8_BAR; PG8_MMA(0, 0, At, B0); PG8_MMA(0, 1, At, B1); PG8_BAR; PG8_SCHED;
;             PG8_LDA(At, 0, 1); PG8_STAGE(PG8_SB(0, 0), b2, voffB); PG8_STAGE(PG8_SB(0, 1), b2 + hstepB, voffB); PG8_STAGE(PG8_SA(0, 0), a2, voffA);
;             PG8_WAIT_V(8); PG8_WAIT_L(0); PG8_BAR; PG8_MMA(1, 0, At, B0); PG8_MMA(1, 1, At, B1); PG8_BAR; PG8_SCHED;
.LBB0_177:
	v_add_u32_e32 v142, s39, v177
	v_add_u32_e32 v182, s24, v177
	s_waitcnt lgkmcnt(0)
	ds_read_b128 v[130:133], v142
	ds_read_b128 v[134:137], v142 offset:1024
	ds_read_b128 v[138:141], v142 offset:2048
	ds_read_b128 v[142:145], v142 offset:3072
	ds_read_b128 v[146:149], v182
	ds_read_b128 v[150:153], v182 offset:1024
	ds_read_b128 v[154:157], v182 offset:2048
	ds_read_b128 v[182:185], v182 offset:3072
	s_add_i32 s27, s17, 2
	s_add_u32 s2, s0, 0x80
	s_addc_u32 s3, s1, 0
	s_cmp_eq_u32 s85, s17
	s_cselect_b32 s3, s7, s3
	s_cselect_b32 s2, s6, s2
	s_cselect_b32 s41, s95, s16
	s_cselect_b32 s40, s94, s5
	s_add_i32 m0, s71, 0xc000
	ds_read_b128 v[186:189], v217
	ds_read_b128 v[190:193], v217 offset:1024
	ds_read_b128 v[194:197], v217 offset:2048
	ds_read_b128 v[198:201], v217 offset:3072
	ds_read_b128 v[202:205], v217 offset:4096
	ds_read_b128 v[206:209], v217 offset:5120
	ds_read_b128 v[218:221], v217 offset:6144
	ds_read_b128 v[222:225], v217 offset:7168
	global_load_lds_dwordx4 v178, s[0:1]
	s_add_i32 m0, s71, 0xe000
	s_nop 0
	global_load_lds_dwordx4 v180, s[0:1]
	s_waitcnt vmcnt(8)
	s_waitcnt lgkmcnt(0)
	s_barrier
	s_setprio 1
	s_waitcnt lgkmcnt(0)
	v_mfma_f32_16x16x32_bf16 v[114:117], v[130:133], v[186:189], v[114:117]
	v_mfma_f32_16x16x32_bf16 v[126:129], v[138:141], v[186:189], v[126:129]
	v_mfma_f32_16x16x32_bf16 v[110:113], v[130:133], v[194:197], v[110:113]
	v_mfma_f32_16x16x32_bf16 v[102:105], v[138:141], v[194:197], v[102:105]
	v_mfma_f32_16x16x32_bf16 v[94:97], v[130:133], v[202:205], v[94:97]
	v_mfma_f32_16x16x32_bf16 v[86:89], v[138:141], v[202:205], v[86:89]
	v_mfma_f32_16x16x32_bf16 v[78:81], v[130:133], v[218:221], v[78:81]
	v_mfma_f32_16x16x32_bf16 v[70:73], v[138:141], v[218:221], v[70:73]
	v_mfma_f32_16x16x32_bf16 v[114:117], v[134:137], v[190:193], v[114:117]
	v_mfma_f32_16x16x32_bf16 v[126:129], v[142:145], v[190:193], v[126:129]
	v_mfma_f32_16x16x32_bf16 v[110:113], v[134:137], v[198:201], v[110:113]
	v_mfma_f32_16x16x32_bf16 v[102:105], v[142:145], v[198:201], v[102:105]
	v_mfma_f32_16x16x32_bf16 v[94:97], v[134:137], v[206:209], v[94:97]
	v_mfma_f32_16x16x32_bf16 v[86:89], v[142:145], v[206:209], v[86:89]
	v_mfma_f32_16x16x32_bf16 v[78:81], v[134:137], v[222:225], v[78:81]
	v_mfma_f32_16x16x32_bf16 v[70:73], v[142:145], v[222:225], v[70:73]
	s_setprio 0
	s_setprio 1
	v_mfma_f32_16x16x32_bf16 v[122:125], v[146:149], v[186:189], v[122:125]
	v_mfma_f32_16x16x32_bf16 v[118:121], v[154:157], v[186:189], v[118:121]
	v_mfma_f32_16x16x32_bf16 v[106:109], v[146:149], v[194:197], v[106:109]
	v_mfma_f32_16x16x32_bf16 v[98:101], v[154:157], v[194:197], v[98:101]
	v_mfma_f32_16x16x32_bf16 v[90:93], v[146:149], v[202:205], v[90:93]
	v_mfma_f32_16x16x32_bf16 v[82:85], v[154:157], v[202:205], v[82:85]
	v_mfma_f32_16x16x32_bf16 v[74:77], v[146:149], v[218:221], v[74:77]
	v_mfma_f32_16x16x32_bf16 v[66:69], v[154:157], v[218:221], v[66:69]
	v_mfma_f32_16x16x32_bf16 v[122:125], v[150:153], v[190:193], v[122:125]
	v_mfma_f32_16x16x32_bf16 v[118:121], v[182:185], v[190:193], v[118:121]
	v_mfma_f32_16x16x32_bf16 v[106:109], v[150:153], v[198:201], v[106:109]
	v_mfma_f32_16x16x32_bf16 v[98:101], v[182:185], v[198:201], v[98:101]
	v_mfma_f32_16x16x32_bf16 v[90:93], v[150:153], v[206:209], v[90:93]
	v_mfma_f32_16x16x32_bf16 v[82:85], v[182:185], v[206:209], v[82:85]
	v_mfma_f32_16x16x32_bf16 v[74:77], v[150:153], v[222:225], v[74:77]
	v_mfma_f32_16x16x32_bf16 v[66:69], v[182:185], v[222:225], v[66:69]
	s_setprio 0
	s_barrier
	s_add_i32 s17, s39, s70
	s_mov_b32 m0, s17
	ds_read_b128 v[186:189], v217 offset:16384
	ds_read_b128 v[190:193], v217 offset:17408
	ds_read_b128 v[194:197], v217 offset:18432
	ds_read_b128 v[198:201], v217 offset:19456
	ds_read_b128 v[202:205], v217 offset:20480
	ds_read_b128 v[206:209], v217 offset:21504
	ds_read_b128 v[218:221], v217 offset:22528
	ds_read_b128 v[222:225], v217 offset:23552
	global_load_lds_dwordx4 v160, s[40:41]
	s_add_i32 m0, s17, 0x2000
	s_add_i32 s17, s24, s70
	global_load_lds_dwordx4 v164, s[40:41]
	s_add_u32 s40, s40, s52
	s_addc_u32 s41, s41, s53
	s_mov_b32 m0, s17
	s_nop 0
	global_load_lds_dwordx4 v160, s[40:41]
	s_add_i32 m0, s17, 0x2000
	s_nop 0
	global_load_lds_dwordx4 v164, s[40:41]
	s_mov_b32 m0, s71
	s_nop 0
	global_load_lds_dwordx4 v158, s[2:3]
	s_mov_b32 m0, s34
	s_nop 0
	global_load_lds_dwordx4 v162, s[2:3]
	s_waitcnt vmcnt(8)
	s_waitcnt lgkmcnt(0)
	s_barrier
	s_setprio 1
	s_waitcnt lgkmcnt(0)
	v_mfma_f32_16x16x32_bf16 v[62:65], v[130:133], v[186:189], v[62:65]
	v_mfma_f32_16x16x32_bf16 v[54:57], v[138:141], v[186:189], v[54:57]
	v_mfma_f32_16x16x32_bf16 v[46:49], v[130:133], v[194:197], v[46:49]
	v_mfma_f32_16x16x32_bf16 v[38:41], v[138:141], v[194:197], v[38:41]
	v_mfma_f32_16x16x32_bf16 v[30:33], v[130:133], v[202:205], v[30:33]
	v_mfma_f32_16x16x32_bf16 v[22:25], v[138:141], v[202:205], v[22:25]
	v_mfma_f32_16x16x32_bf16 v[14:17], v[130:133], v[218:221], v[14:17]
	v_mfma_f32_16x16x32_bf16 v[6:9], v[138:141], v[218:221], v[6:9]
	v_mfma_f32_16x16x32_bf16 v[62:65], v[134:137], v[190:193], v[62:65]
	v_mfma_f32_16x16x32_bf16 v[54:57], v[142:145], v[190:193], v[54:57]
	v_mfma_f32_16x16x32_bf16 v[46:49], v[134:137], v[198:201], v[46:49]
	v_mfma_f32_16x16x32_bf16 v[38:41], v[142:145], v[198:201], v[38:41]
	v_mfma_f32_16x16x32_bf16 v[30:33], v[134:137], v[206:209], v[30:33]
	v_mfma_f32_16x16x32_bf16 v[22:25], v[142:145], v[206:209], v[22:25]
	v_mfma_f32_16x16x32_bf16 v[14:17], v[134:137], v[222:225], v[14:17]
	v_mfma_f32_16x16x32_bf16 v[6:9], v[142:145], v[222:225], v[6:9]
	s_setprio 0
	s_setprio 1
	v_mfma_f32_16x16x32_bf16 v[58:61], v[146:149], v[186:189], v[58:61]
	v_mfma_f32_16x16x32_bf16 v[50:53], v[154:157], v[186:189], v[50:53]
	v_mfma_f32_16x16x32_bf16 v[42:45], v[146:149], v[194:197], v[42:45]
	v_mfma_f32_16x16x32_bf16 v[34:37], v[154:157], v[194:197], v[34:37]
	v_mfma_f32_16x16x32_bf16 v[26:29], v[146:149], v[202:205], v[26:29]
	v_mfma_f32_16x16x32_bf16 v[18:21], v[154:157], v[202:205], v[18:21]
	v_mfma_f32_16x16x32_bf16 v[10:13], v[146:149], v[218:221], v[10:13]
	v_mfma_f32_16x16x32_bf16 v[2:5], v[154:157], v[218:221], v[2:5]
	v_mfma_f32_16x16x32_bf16 v[58:61], v[150:153], v[190:193], v[58:61]
	v_mfma_f32_16x16x32_bf16 v[50:53], v[182:185], v[190:193], v[50:53]
	v_mfma_f32_16x16x32_bf16 v[42:45], v[150:153], v[198:201], v[42:45]
	v_mfma_f32_16x16x32_bf16 v[34:37], v[182:185], v[198:201], v[34:37]
	v_mfma_f32_16x16x32_bf16 v[26:29], v[150:153], v[206:209], v[26:29]
	v_mfma_f32_16x16x32_bf16 v[18:21], v[182:185], v[206:209], v[18:21]
	v_mfma_f32_16x16x32_bf16 v[10:13], v[150:153], v[222:225], v[10:13]
	v_mfma_f32_16x16x32_bf16 v[2:5], v[182:185], v[222:225], v[2:5]
	s_setprio 0
	s_barrier
; #define PG8_STAGE(bufoff, gbase, voff) do { _Pragma("unroll") for (int _i = 0; _i < 2; ++_i) \
;         __builtin_amdgcn_global_load_lds((const unsigned*)((const char*)(gbase) + (voff)[_i]), (LAS unsigned*)(lds + (bufoff) + ldsw + _i * 8192), 16, 0, 0); } while (0)
; #define PG8_LDA(dst, b, h) do { _Pragma("unroll") for (int m = 0; m < 4; ++m) _Pragma("unroll") for (int k = 0; k < 2; ++k) dst[m][k] = *(const LAS bf16x8*)(lds + PG8_SA(b, h) + aoff + m * 2048 + k * 1024); } while (0)
; #define PG8_LDB(dst, b, h) do { _Pragma("unroll") for (int n = 0; n < 2; ++n) _Pragma("unroll") for (int k = 0; k < 2; ++k) dst[n][k] = *(const LAS bf16x8*)(lds + PG8_SB(b, h) + boff + n * 2048 + k * 1024); } while (0)
; #define PG8_MMA(ai, bj, At, Bt) do { __builtin_amdgcn_s_setprio(1); _Pragma("unroll") for (int m = 0; m < 4; ++m) _Pragma("unroll") for (int n = 0; n < 2; ++n) _Pragma("unroll") for (int k = 0; k < 2; ++k) \
;         acc[ai][bj][m][n] = __builtin_amdgcn_mfma_f32_16x16x32_bf16(Bt[n][k], At[m][k], acc[ai][bj][m][n], 0, 0, 0); __builtin_amdgcn_s_setprio(0); } while (0)
; #define PG8_WAIT_V(n) asm volatile("s_waitcnt vmcnt(" #n ")" ::: "memory")
; #define PG8_WAIT_L(n) asm volatile("s_waitcnt lgkmcnt(" #n ")" ::: "memory")
; #define PG8_BAR __builtin_amdgcn_s_barrier()
; #define PG8_SCHED __builtin_amdgcn_sched_barrier(0)
; __device__ __forceinline__ void gemm_phase(LAS unsigned char* lds, const Gemm g, const StaticOrder& S, const Epi& E) {
;     ...
;             PG8_LDB(B0, 1, 0); PG8_LDB(B1, 1, 1); PG8_SCHED; PG8_LDA(At, 1, 0); PG8_STAGE(PG8_SA(0, 1), a2 + hstepA, voffA);
;             PG8_WAIT_V(8); PG8_WAIT_L(0); PG8_BAR; PG8_MMA(0, 0, At, B0); PG8_MMA(0, 1, At, B1); PG8_BAR; PG8_SCHED;
;             PG8_LDA(At, 1, 1); PG8_STAGE(PG8_SB(1, 0), b3, voffB); PG8_STAGE(PG8_SB(1, 1), b3 + hstepB, voffB); PG8_STAGE(PG8_SA(1, 0), a3, voffA);
;             PG8_WAIT_V(8); PG8_WAIT_L(0); PG8_BAR; PG8_MMA(1, 0, At, B0); PG8_MMA(1, 1, At, B1); PG8_BAR; PG8_SCHED;
	v_add_u32_e32 v142, s25, v177
	v_add_u32_e32 v182, s26, v177
	ds_read_b128 v[130:133], v142
	ds_read_b128 v[134:137], v142 offset:1024
	ds_read_b128 v[138:141], v142 offset:2048
	ds_read_b128 v[142:145], v142 offset:3072
	ds_read_b128 v[146:149], v182
	ds_read_b128 v[150:153], v182 offset:1024
	ds_read_b128 v[154:157], v182 offset:2048
	ds_read_b128 v[182:185], v182 offset:3072
	s_add_u32 s2, s2, s50
	s_addc_u32 s3, s3, s51
	s_mov_b32 m0, s92
	ds_read_b128 v[186:189], v217 offset:32768
	ds_read_b128 v[190:193], v217 offset:33792
	ds_read_b128 v[194:197], v217 offset:34816
	ds_read_b128 v[198:201], v217 offset:35840
	ds_read_b128 v[202:205], v217 offset:36864
	ds_read_b128 v[206:209], v217 offset:37888
	ds_read_b128 v[218:221], v217 offset:38912
	ds_read_b128 v[222:225], v217 offset:39936
	global_load_lds_dwordx4 v158, s[2:3]
	s_mov_b32 m0, s93
	s_nop 0
	global_load_lds_dwordx4 v162, s[2:3]
	s_waitcnt vmcnt(8)
	s_waitcnt lgkmcnt(0)
	s_barrier
	s_setprio 1
	s_waitcnt lgkmcnt(0)
	v_mfma_f32_16x16x32_bf16 v[114:117], v[130:133], v[186:189], v[114:117]
	v_mfma_f32_16x16x32_bf16 v[126:129], v[138:141], v[186:189], v[126:129]
	v_mfma_f32_16x16x32_bf16 v[110:113], v[130:133], v[194:197], v[110:113]
	v_mfma_f32_16x16x32_bf16 v[102:105], v[138:141], v[194:197], v[102:105]
	v_mfma_f32_16x16x32_bf16 v[94:97], v[130:133], v[202:205], v[94:97]
	v_mfma_f32_16x16x32_bf16 v[86:89], v[138:141], v[202:205], v[86:89]
	v_mfma_f32_16x16x32_bf16 v[78:81], v[130:133], v[218:221], v[78:81]
	v_mfma_f32_16x16x32_bf16 v[70:73], v[138:141], v[218:221], v[70:73]
	v_mfma_f32_16x16x32_bf16 v[114:117], v[134:137], v[190:193], v[114:117]
	v_mfma_f32_16x16x32_bf16 v[126:129], v[142:145], v[190:193], v[126:129]
	v_mfma_f32_16x16x32_bf16 v[110:113], v[134:137], v[198:201], v[110:113]
	v_mfma_f32_16x16x32_bf16 v[102:105], v[142:145], v[198:201], v[102:105]
	v_mfma_f32_16x16x32_bf16 v[94:97], v[134:137], v[206:209], v[94:97]
	v_mfma_f32_16x16x32_bf16 v[86:89], v[142:145], v[206:209], v[86:89]
	v_mfma_f32_16x16x32_bf16 v[78:81], v[134:137], v[222:225], v[78:81]
	v_mfma_f32_16x16x32_bf16 v[70:73], v[142:145], v[222:225], v[70:73]
	s_setprio 0
	s_setprio 1
	v_mfma_f32_16x16x32_bf16 v[122:125], v[146:149], v[186:189], v[122:125]
	v_mfma_f32_16x16x32_bf16 v[118:121], v[154:157], v[186:189], v[118:121]
	v_mfma_f32_16x16x32_bf16 v[106:109], v[146:149], v[194:197], v[106:109]
	v_mfma_f32_16x16x32_bf16 v[98:101], v[154:157], v[194:197], v[98:101]
	v_mfma_f32_16x16x32_bf16 v[90:93], v[146:149], v[202:205], v[90:93]
	v_mfma_f32_16x16x32_bf16 v[82:85], v[154:157], v[202:205], v[82:85]
	v_mfma_f32_16x16x32_bf16 v[74:77], v[146:149], v[218:221], v[74:77]
	v_mfma_f32_16x16x32_bf16 v[66:69], v[154:157], v[218:221], v[66:69]
	v_mfma_f32_16x16x32_bf16 v[122:125], v[150:153], v[190:193], v[122:125]
	v_mfma_f32_16x16x32_bf16 v[118:121], v[182:185], v[190:193], v[118:121]
	v_mfma_f32_16x16x32_bf16 v[106:109], v[150:153], v[198:201], v[106:109]
	v_mfma_f32_16x16x32_bf16 v[98:101], v[182:185], v[198:201], v[98:101]
	v_mfma_f32_16x16x32_bf16 v[90:93], v[150:153], v[206:209], v[90:93]
	v_mfma_f32_16x16x32_bf16 v[82:85], v[182:185], v[206:209], v[82:85]
	v_mfma_f32_16x16x32_bf16 v[74:77], v[150:153], v[222:225], v[74:77]
	v_mfma_f32_16x16x32_bf16 v[66:69], v[182:185], v[222:225], v[66:69]
	s_setprio 0
	s_barrier
	s_add_u32 s40, s40, 0x80
	s_addc_u32 s41, s41, 0
	s_sub_u32 s100, s40, s52
	s_subb_u32 s101, s41, s53
	s_sub_u32 s2, s2, s50
	s_subb_u32 s3, s3, s51
	s_add_u32 s2, s2, 0x80
	s_addc_u32 s3, s3, 0
	s_add_i32 vcc_lo, s25, s70
	s_mov_b32 m0, vcc_lo
	ds_read_b128 v[186:189], v217 offset:49152
	ds_read_b128 v[190:193], v217 offset:50176
	ds_read_b128 v[194:197], v217 offset:51200
	ds_read_b128 v[198:201], v217 offset:52224
	ds_read_b128 v[202:205], v217 offset:53248
	ds_read_b128 v[206:209], v217 offset:54272
	ds_read_b128 v[218:221], v217 offset:55296
	ds_read_b128 v[222:225], v217 offset:56320
	global_load_lds_dwordx4 v160, s[100:101]
	s_add_i32 m0, vcc_lo, 0x2000
	s_add_i32 vcc_lo, s26, s70
	global_load_lds_dwordx4 v164, s[100:101]
	s_mov_b32 m0, vcc_lo
	s_nop 0
	global_load_lds_dwordx4 v160, s[40:41]
	s_add_i32 m0, vcc_lo, 0x2000
	s_nop 0
	global_load_lds_dwordx4 v164, s[40:41]
	s_mov_b32 m0, s58
	s_nop 0
	global_load_lds_dwordx4 v158, s[2:3]
	s_mov_b32 m0, s59
	s_nop 0
	global_load_lds_dwordx4 v162, s[2:3]
	s_waitcnt vmcnt(8)
	s_waitcnt lgkmcnt(0)
	s_barrier
	s_setprio 1
	s_waitcnt lgkmcnt(0)
	v_mfma_f32_16x16x32_bf16 v[62:65], v[130:133], v[186:189], v[62:65]
	v_mfma_f32_16x16x32_bf16 v[54:57], v[138:141], v[186:189], v[54:57]
	v_mfma_f32_16x16x32_bf16 v[46:49], v[130:133], v[194:197], v[46:49]
	v_mfma_f32_16x16x32_bf16 v[38:41], v[138:141], v[194:197], v[38:41]
	v_mfma_f32_16x16x32_bf16 v[30:33], v[130:133], v[202:205], v[30:33]
	v_mfma_f32_16x16x32_bf16 v[22:25], v[138:141], v[202:205], v[22:25]
	v_mfma_f32_16x16x32_bf16 v[14:17], v[130:133], v[218:221], v[14:17]
	v_mfma_f32_16x16x32_bf16 v[6:9], v[138:141], v[218:221], v[6:9]
	v_mfma_f32_16x16x32_bf16 v[62:65], v[134:137], v[190:193], v[62:65]
	v_mfma_f32_16x16x32_bf16 v[54:57], v[142:145], v[190:193], v[54:57]
	v_mfma_f32_16x16x32_bf16 v[46:49], v[134:137], v[198:201], v[46:49]
	v_mfma_f32_16x16x32_bf16 v[38:41], v[142:145], v[198:201], v[38:41]
	v_mfma_f32_16x16x32_bf16 v[30:33], v[134:137], v[206:209], v[30:33]
	v_mfma_f32_16x16x32_bf16 v[22:25], v[142:145], v[206:209], v[22:25]
	v_mfma_f32_16x16x32_bf16 v[14:17], v[134:137], v[222:225], v[14:17]
	v_mfma_f32_16x16x32_bf16 v[6:9], v[142:145], v[222:225], v[6:9]
	s_setprio 0
	s_setprio 1
	v_mfma_f32_16x16x32_bf16 v[58:61], v[146:149], v[186:189], v[58:61]
	v_mfma_f32_16x16x32_bf16 v[50:53], v[154:157], v[186:189], v[50:53]
	v_mfma_f32_16x16x32_bf16 v[42:45], v[146:149], v[194:197], v[42:45]
	v_mfma_f32_16x16x32_bf16 v[34:37], v[154:157], v[194:197], v[34:37]
	v_mfma_f32_16x16x32_bf16 v[26:29], v[146:149], v[202:205], v[26:29]
	v_mfma_f32_16x16x32_bf16 v[18:21], v[154:157], v[202:205], v[18:21]
	v_mfma_f32_16x16x32_bf16 v[10:13], v[146:149], v[218:221], v[10:13]
	v_mfma_f32_16x16x32_bf16 v[2:5], v[154:157], v[218:221], v[2:5]
	v_mfma_f32_16x16x32_bf16 v[58:61], v[150:153], v[190:193], v[58:61]
	v_mfma_f32_16x16x32_bf16 v[50:53], v[182:185], v[190:193], v[50:53]
	v_mfma_f32_16x16x32_bf16 v[42:45], v[150:153], v[198:201], v[42:45]
	v_mfma_f32_16x16x32_bf16 v[34:37], v[182:185], v[198:201], v[34:37]
	v_mfma_f32_16x16x32_bf16 v[26:29], v[150:153], v[206:209], v[26:29]
	v_mfma_f32_16x16x32_bf16 v[18:21], v[182:185], v[206:209], v[18:21]
	v_mfma_f32_16x16x32_bf16 v[10:13], v[150:153], v[222:225], v[10:13]
	v_mfma_f32_16x16x32_bf16 v[2:5], v[182:185], v[222:225], v[2:5]
	s_setprio 0
	s_barrier
	s_add_u32 s0, s0, 0x100
	s_addc_u32 s1, s1, 0
	s_add_u32 s5, s5, 0x100
	s_addc_u32 s16, s16, 0
	s_cmp_ge_i32 s27, s84
	s_mov_b32 s17, s27
	s_cbranch_scc0 .LBB0_177
	s_and_b64 vcc, exec, s[74:75]
	s_cbranch_vccz .LBB0_180

; template <int MODE, bool NOMAX = false> ...
;     ...
;                     f32x16 negm;
;                     { const float nm = NOMAX ? cq : cq - mhat;
; #pragma unroll
;                       for (int r = 0; r < 16; ++r) negm[r] = nm; }
;                     asm volatile("" : "+v"(negm));
;                     qkt(p0, p1, kb, qr, negm);
;                     if (MODE == 1) {
; #pragma unroll
;                         for (int g = 0; g < 4; ++g) {
;                             const f32x4 c0 = *(const LAS f32x4*)(cum + kt * 64 + 8 * g + 4 * hi), c1 = *(const LAS f32x4*)(cum + kt * 64 + 32 + 8 * g + 4 * hi);
; #pragma unroll
;                             for (int i = 0; i < 4; ++i) { p0[4 * g + i] -= c0[i]; p1[4 * g + i] -= c1[i]; }
;                         }
;                         if (diag) {
; #pragma unroll
;                             for (int r = 0; r < 16; ++r) { const int kv = crow(r, hi); if (kv > trel) p0[r] = -INFINITY; if (kv + 32 > trel) p1[r] = -INFINITY; }
;                         }
;                     }
;                     const float rm = NOMAX ? 0.f : rowmax(p0, p1);
;                     if (NOMAX) {
;                     } else if (it == it0) {
;                         mhat = rm;
; #pragma unroll
;                         for (int r = 0; r < 16; ++r) { p0[r] -= rm; p1[r] -= rm; }
;                     } else if (__any(rm > 8.0f)) {
;                         const float dl = fmaxf(rm, 0.f); mhat += dl;
; #pragma unroll
;                         for (int r = 0; r < 16; ++r) { p0[r] -= dl; p1[r] -= dl; }
;                         const float f = __builtin_amdgcn_exp2f(-dl); l_reg *= f;
;                         if (hi == 0) wsf[r32] = f;
;                         asm volatile("s_waitcnt lgkmcnt(0)" ::: "memory");
; #pragma unroll
;                         for (int g = 0; g < 4; ++g) { const f32x4 fv = *(const LAS f32x4*)(wsf + 8 * g + 4 * hi);
; #pragma unroll
;                             for (int d = 0; d < ND; ++d)
; #pragma unroll
;                                 for (int i = 0; i < 4; ++i) o[d][4 * g + i] *= fv[i]; }
;                     }
;                     float sacc = 0.f;
; #pragma unroll
;                     for (int r = 0; r < 16; ++r) { p0[r] = __builtin_amdgcn_exp2f(p0[r]); p1[r] = __builtin_amdgcn_exp2f(p1[r]); sacc += p0[r] + p1[r]; }
;                     l_reg += sacc;
;                 }
.LBB0_1073:
	s_cmp_gt_i32 s16, s5
	s_cbranch_scc1 .LBB0_1078
	v_add_u32_e32 v166, s27, v202
	ds_read_b128 v[2:5], v166
	ds_read_b128 v[6:9], v166 offset:512
	s_waitcnt lgkmcnt(1)
	v_mfma_f32_32x32x16_bf16 v[96:111], v[2:5], v[140:143], 0
	s_andn2_b64 vcc, exec, s[2:3]
	s_waitcnt lgkmcnt(0)
	v_mfma_f32_32x32x16_bf16 v[80:95], v[6:9], v[140:143], 0
	ds_read_b128 v[2:5], v166 offset:2048
	ds_read_b128 v[6:9], v166 offset:2560
	s_waitcnt lgkmcnt(1)
	v_mfma_f32_32x32x16_bf16 v[96:111], v[2:5], v[136:139], v[96:111]
	s_waitcnt lgkmcnt(0)
	v_mfma_f32_32x32x16_bf16 v[80:95], v[6:9], v[136:139], v[80:95]
	ds_read_b128 v[2:5], v166 offset:4096
	ds_read_b128 v[6:9], v166 offset:4608
	s_waitcnt lgkmcnt(1)
	v_mfma_f32_32x32x16_bf16 v[96:111], v[2:5], v[132:135], v[96:111]
	s_waitcnt lgkmcnt(0)
	v_mfma_f32_32x32x16_bf16 v[80:95], v[6:9], v[132:135], v[80:95]
	ds_read_b128 v[2:5], v166 offset:6144
	ds_read_b128 v[6:9], v166 offset:6656
	s_waitcnt lgkmcnt(1)
	v_mfma_f32_32x32x16_bf16 v[96:111], v[2:5], v[128:131], v[96:111]
	s_waitcnt lgkmcnt(0)
	v_mfma_f32_32x32x16_bf16 v[80:95], v[6:9], v[128:131], v[80:95]
	s_nop 9
	v_exp_f32_e32 v183, v96
	v_exp_f32_e32 v182, v97
	v_exp_f32_e32 v179, v98
	v_exp_f32_e32 v178, v99
	v_exp_f32_e32 v167, v100
	v_exp_f32_e32 v166, v101
	v_exp_f32_e32 v97, v102
	v_exp_f32_e32 v185, v80
	v_exp_f32_e32 v184, v81
	v_exp_f32_e32 v181, v82
	v_exp_f32_e32 v180, v83
	v_exp_f32_e32 v177, v84
	v_exp_f32_e32 v176, v85
	v_exp_f32_e32 v99, v86
	v_exp_f32_e32 v98, v103
	v_exp_f32_e32 v100, v87
	v_exp_f32_e32 v13, v104
	v_exp_f32_e32 v15, v88
	v_exp_f32_e32 v14, v105
	v_exp_f32_e32 v96, v89
	v_exp_f32_e32 v9, v106
	v_exp_f32_e32 v11, v90
	v_exp_f32_e32 v10, v107
	v_exp_f32_e32 v12, v91
	v_exp_f32_e32 v5, v108
	v_exp_f32_e32 v7, v92
	v_exp_f32_e32 v6, v109
	v_exp_f32_e32 v8, v93
	v_exp_f32_e32 v1, v110
	v_exp_f32_e32 v3, v94
	v_exp_f32_e32 v2, v111
	v_exp_f32_e32 v4, v95
	v_cvt_pk_bf16_f32 v80, v183, v182
	v_cvt_pk_bf16_f32 v81, v179, v178
	v_cvt_pk_bf16_f32 v82, v167, v166
	v_cvt_pk_bf16_f32 v83, v97, v98
	v_cvt_pk_bf16_f32 v84, v13, v14
	v_cvt_pk_bf16_f32 v85, v9, v10
	v_cvt_pk_bf16_f32 v86, v5, v6
	v_cvt_pk_bf16_f32 v87, v1, v2
	v_cvt_pk_bf16_f32 v88, v185, v184
	v_cvt_pk_bf16_f32 v89, v181, v180
	v_cvt_pk_bf16_f32 v90, v177, v176
	v_cvt_pk_bf16_f32 v91, v99, v100
	v_cvt_pk_bf16_f32 v92, v15, v96
	v_cvt_pk_bf16_f32 v93, v11, v12
	v_cvt_pk_bf16_f32 v94, v7, v8
	v_cvt_pk_bf16_f32 v95, v3, v4
	s_cbranch_vccnz .LBB0_1076
	v_lshl_add_u32 v101, s21, 14, v189
	ds_read_b64_tr_b16 v[102:103],v101 offset:0
	ds_read_b64_tr_b16 v[104:105],v101 offset:512
	ds_read_b64_tr_b16 v[106:107],v101 offset:1024
	ds_read_b64_tr_b16 v[108:109],v101 offset:1536
	ds_read_b64_tr_b16 v[218:219],v101 offset:2048
	ds_read_b64_tr_b16 v[220:221],v101 offset:2560
	ds_read_b64_tr_b16 v[222:223],v101 offset:3072
	ds_read_b64_tr_b16 v[224:225],v101 offset:3584
	ds_read_b64_tr_b16 v[226:227],v101 offset:4096
	ds_read_b64_tr_b16 v[228:229],v101 offset:4608
	ds_read_b64_tr_b16 v[230:231],v101 offset:5120
	ds_read_b64_tr_b16 v[232:233],v101 offset:5632
	ds_read_b64_tr_b16 v[234:235],v101 offset:6144
	ds_read_b64_tr_b16 v[236:237],v101 offset:6656
	ds_read_b64_tr_b16 v[238:239],v101 offset:7168
	ds_read_b64_tr_b16 v[240:241],v101 offset:7680
	s_waitcnt lgkmcnt(0)
	s_nop 0
	v_mfma_f32_32x32x16_bf16 v[32:47], v[80:83], v[102:105], v[32:47]
	v_add_u32_e32 v101, 0x2000, v101
	ds_read_b64_tr_b16 v[102:103],v101 offset:0
	ds_read_b64_tr_b16 v[104:105],v101 offset:512
	v_mfma_f32_32x32x16_bf16 v[16:31], v[80:83], v[226:229], v[16:31]
	v_mfma_f32_32x32x16_bf16 v[32:47], v[84:87], v[106:109], v[32:47]
	ds_read_b64_tr_b16 v[106:107],v101 offset:1024
	ds_read_b64_tr_b16 v[108:109],v101 offset:1536
	v_mfma_f32_32x32x16_bf16 v[16:31], v[84:87], v[230:233], v[16:31]
	v_mfma_f32_32x32x16_bf16 v[32:47], v[88:91], v[218:221], v[32:47]
	ds_read_b64_tr_b16 v[218:219],v101 offset:2048
	ds_read_b64_tr_b16 v[220:221],v101 offset:2560
	v_mfma_f32_32x32x16_bf16 v[16:31], v[88:91], v[234:237], v[16:31]
	v_mfma_f32_32x32x16_bf16 v[32:47], v[92:95], v[222:225], v[32:47]
	ds_read_b64_tr_b16 v[222:223],v101 offset:3072
	ds_read_b64_tr_b16 v[224:225],v101 offset:3584
	ds_read_b64_tr_b16 v[226:227],v101 offset:4096
	ds_read_b64_tr_b16 v[228:229],v101 offset:4608
	ds_read_b64_tr_b16 v[230:231],v101 offset:5120
	ds_read_b64_tr_b16 v[232:233],v101 offset:5632
	ds_read_b64_tr_b16 v[234:235],v101 offset:6144
	v_mfma_f32_32x32x16_bf16 v[16:31], v[92:95], v[238:241], v[16:31]
	ds_read_b64_tr_b16 v[236:237],v101 offset:6656
	ds_read_b64_tr_b16 v[238:239],v101 offset:7168
	ds_read_b64_tr_b16 v[240:241],v101 offset:7680
	s_waitcnt lgkmcnt(0)
	v_mfma_f32_32x32x16_bf16 v[48:63], v[80:83], v[102:105], v[48:63]
	v_mfma_f32_32x32x16_bf16 v[64:79], v[80:83], v[226:229], v[64:79]
	v_mfma_f32_32x32x16_bf16 v[48:63], v[84:87], v[106:109], v[48:63]
	v_mfma_f32_32x32x16_bf16 v[64:79], v[84:87], v[230:233], v[64:79]
	v_mfma_f32_32x32x16_bf16 v[48:63], v[88:91], v[218:221], v[48:63]
	v_mfma_f32_32x32x16_bf16 v[64:79], v[88:91], v[234:237], v[64:79]
	v_mfma_f32_32x32x16_bf16 v[48:63], v[92:95], v[222:225], v[48:63]
	v_mfma_f32_32x32x16_bf16 v[64:79], v[92:95], v[238:241], v[64:79]
	s_branch .LBB0_1077

; template <int MODE, bool NOMAX = false> ...
;     ...
;                     f32x16 negm;
;                     { const float nm = NOMAX ? cq : cq - mhat;
; #pragma unroll
;                       for (int r = 0; r < 16; ++r) negm[r] = nm; }
;                     asm volatile("" : "+v"(negm));
;                     qkt(p0, p1, kb, qr, negm);
;                     if (MODE == 1) {
; #pragma unroll
;                         for (int g = 0; g < 4; ++g) {
;                             const f32x4 c0 = *(const LAS f32x4*)(cum + kt * 64 + 8 * g + 4 * hi), c1 = *(const LAS f32x4*)(cum + kt * 64 + 32 + 8 * g + 4 * hi);
; #pragma unroll
;                             for (int i = 0; i < 4; ++i) { p0[4 * g + i] -= c0[i]; p1[4 * g + i] -= c1[i]; }
;                         }
;                         if (diag) {
; #pragma unroll
;                             for (int r = 0; r < 16; ++r) { const int kv = crow(r, hi); if (kv > trel) p0[r] = -INFINITY; if (kv + 32 > trel) p1[r] = -INFINITY; }
;                         }
;                     }
;                     const float rm = NOMAX ? 0.f : rowmax(p0, p1);
;                     if (NOMAX) {
;                     } else if (it == it0) {
;                         mhat = rm;
; #pragma unroll
;                         for (int r = 0; r < 16; ++r) { p0[r] -= rm; p1[r] -= rm; }
;                     } else if (__any(rm > 8.0f)) {
;                         const float dl = fmaxf(rm, 0.f); mhat += dl;
; #pragma unroll
;                         for (int r = 0; r < 16; ++r) { p0[r] -= dl; p1[r] -= dl; }
;                         const float f = __builtin_amdgcn_exp2f(-dl); l_reg *= f;
;                         if (hi == 0) wsf[r32] = f;
;                         asm volatile("s_waitcnt lgkmcnt(0)" ::: "memory");
; #pragma unroll
;                         for (int g = 0; g < 4; ++g) { const f32x4 fv = *(const LAS f32x4*)(wsf + 8 * g + 4 * hi);
; #pragma unroll
;                             for (int d = 0; d < ND; ++d)
; #pragma unroll
;                                 for (int i = 0; i < 4; ++i) o[d][4 * g + i] *= fv[i]; }
;                     }
;                     float sacc = 0.f;
; #pragma unroll
;                     for (int r = 0; r < 16; ++r) { p0[r] = __builtin_amdgcn_exp2f(p0[r]); p1[r] = __builtin_amdgcn_exp2f(p1[r]); sacc += p0[r] + p1[r]; }
;                     l_reg += sacc;
;                 }
.LBB0_1096:
	s_cmp_gt_i32 s17, s5
	s_cbranch_scc1 .LBB0_1101
	v_add_u32_e32 v122, s21, v202
	ds_read_b128 v[2:5], v122
	ds_read_b128 v[6:9], v122 offset:512
	s_waitcnt lgkmcnt(1)
	v_mfma_f32_32x32x16_bf16 v[96:111], v[2:5], v[128:131], 0
	s_and_b64 vcc, exec, s[42:43]
	s_waitcnt lgkmcnt(0)
	v_mfma_f32_32x32x16_bf16 v[80:95], v[6:9], v[128:131], 0
	ds_read_b128 v[2:5], v122 offset:2048
	ds_read_b128 v[6:9], v122 offset:2560
	s_waitcnt lgkmcnt(1)
	v_mfma_f32_32x32x16_bf16 v[96:111], v[2:5], v[140:143], v[96:111]
	s_waitcnt lgkmcnt(0)
	v_mfma_f32_32x32x16_bf16 v[80:95], v[6:9], v[140:143], v[80:95]
	ds_read_b128 v[2:5], v122 offset:4096
	ds_read_b128 v[6:9], v122 offset:4608
	s_waitcnt lgkmcnt(1)
	v_mfma_f32_32x32x16_bf16 v[96:111], v[2:5], v[136:139], v[96:111]
	s_waitcnt lgkmcnt(0)
	v_mfma_f32_32x32x16_bf16 v[80:95], v[6:9], v[136:139], v[80:95]
	ds_read_b128 v[2:5], v122 offset:6144
	ds_read_b128 v[6:9], v122 offset:6656
	s_waitcnt lgkmcnt(1)
	v_mfma_f32_32x32x16_bf16 v[96:111], v[2:5], v[132:135], v[96:111]
	s_waitcnt lgkmcnt(0)
	v_mfma_f32_32x32x16_bf16 v[80:95], v[6:9], v[132:135], v[80:95]
	s_nop 9
	v_exp_f32_e32 v151, v96
	v_exp_f32_e32 v150, v97
	v_exp_f32_e32 v127, v98
	v_exp_f32_e32 v126, v99
	v_exp_f32_e32 v123, v100
	v_exp_f32_e32 v122, v101
	v_exp_f32_e32 v97, v102
	v_exp_f32_e32 v153, v80
	v_exp_f32_e32 v152, v81
	v_exp_f32_e32 v149, v82
	v_exp_f32_e32 v148, v83
	v_exp_f32_e32 v125, v84
	v_exp_f32_e32 v124, v85
	v_exp_f32_e32 v99, v86
	v_exp_f32_e32 v98, v103
	v_exp_f32_e32 v100, v87
	v_exp_f32_e32 v13, v104
	v_exp_f32_e32 v15, v88
	v_exp_f32_e32 v14, v105
	v_exp_f32_e32 v96, v89
	v_exp_f32_e32 v9, v106
	v_exp_f32_e32 v11, v90
	v_exp_f32_e32 v10, v107
	v_exp_f32_e32 v12, v91
	v_exp_f32_e32 v5, v108
	v_exp_f32_e32 v7, v92
	v_exp_f32_e32 v6, v109
	v_exp_f32_e32 v8, v93
	v_exp_f32_e32 v1, v110
	v_exp_f32_e32 v3, v94
	v_exp_f32_e32 v2, v111
	v_exp_f32_e32 v4, v95
	v_cvt_pk_bf16_f32 v80, v151, v150
	v_cvt_pk_bf16_f32 v81, v127, v126
	v_cvt_pk_bf16_f32 v82, v123, v122
	v_cvt_pk_bf16_f32 v83, v97, v98
	v_cvt_pk_bf16_f32 v84, v13, v14
	v_cvt_pk_bf16_f32 v85, v9, v10
	v_cvt_pk_bf16_f32 v86, v5, v6
	v_cvt_pk_bf16_f32 v87, v1, v2
	v_cvt_pk_bf16_f32 v88, v153, v152
	v_cvt_pk_bf16_f32 v89, v149, v148
	v_cvt_pk_bf16_f32 v90, v125, v124
	v_cvt_pk_bf16_f32 v91, v99, v100
	v_cvt_pk_bf16_f32 v92, v15, v96
	v_cvt_pk_bf16_f32 v93, v11, v12
	v_cvt_pk_bf16_f32 v94, v7, v8
	v_cvt_pk_bf16_f32 v95, v3, v4
	s_cbranch_vccnz .LBB0_1099
	v_lshl_add_u32 v101, s19, 14, v189
	ds_read_b64_tr_b16 v[102:103],v101 offset:0
	ds_read_b64_tr_b16 v[104:105],v101 offset:512
	ds_read_b64_tr_b16 v[106:107],v101 offset:1024
	ds_read_b64_tr_b16 v[108:109],v101 offset:1536
	ds_read_b64_tr_b16 v[160:161],v101 offset:2048
	ds_read_b64_tr_b16 v[162:163],v101 offset:2560
	ds_read_b64_tr_b16 v[176:177],v101 offset:3072
	ds_read_b64_tr_b16 v[178:179],v101 offset:3584
	ds_read_b64_tr_b16 v[180:181],v101 offset:4096
	ds_read_b64_tr_b16 v[182:183],v101 offset:4608
	ds_read_b64_tr_b16 v[206:207],v101 offset:5120
	ds_read_b64_tr_b16 v[208:209],v101 offset:5632
	ds_read_b64_tr_b16 v[218:219],v101 offset:6144
	ds_read_b64_tr_b16 v[220:221],v101 offset:6656
	ds_read_b64_tr_b16 v[222:223],v101 offset:7168
	ds_read_b64_tr_b16 v[224:225],v101 offset:7680
	s_waitcnt lgkmcnt(0)
	s_nop 0
	v_mfma_f32_32x32x16_bf16 v[16:31], v[80:83], v[102:105], v[16:31]
	v_add_u32_e32 v101, 0x2000, v101
	ds_read_b64_tr_b16 v[102:103],v101 offset:0
	ds_read_b64_tr_b16 v[104:105],v101 offset:512
	v_mfma_f32_32x32x16_bf16 v[32:47], v[80:83], v[180:183], v[32:47]
	v_mfma_f32_32x32x16_bf16 v[16:31], v[84:87], v[106:109], v[16:31]
	ds_read_b64_tr_b16 v[106:107],v101 offset:1024
	ds_read_b64_tr_b16 v[108:109],v101 offset:1536
	v_mfma_f32_32x32x16_bf16 v[32:47], v[84:87], v[206:209], v[32:47]
	v_mfma_f32_32x32x16_bf16 v[16:31], v[88:91], v[160:163], v[16:31]
	ds_read_b64_tr_b16 v[160:161],v101 offset:2048
	ds_read_b64_tr_b16 v[162:163],v101 offset:2560
	v_mfma_f32_32x32x16_bf16 v[32:47], v[88:91], v[218:221], v[32:47]
	v_mfma_f32_32x32x16_bf16 v[16:31], v[92:95], v[176:179], v[16:31]
	ds_read_b64_tr_b16 v[176:177],v101 offset:3072
	ds_read_b64_tr_b16 v[178:179],v101 offset:3584
	ds_read_b64_tr_b16 v[180:181],v101 offset:4096
	ds_read_b64_tr_b16 v[182:183],v101 offset:4608
	ds_read_b64_tr_b16 v[206:207],v101 offset:5120
	ds_read_b64_tr_b16 v[208:209],v101 offset:5632
	ds_read_b64_tr_b16 v[218:219],v101 offset:6144
	v_mfma_f32_32x32x16_bf16 v[32:47], v[92:95], v[222:225], v[32:47]
	ds_read_b64_tr_b16 v[220:221],v101 offset:6656
	ds_read_b64_tr_b16 v[222:223],v101 offset:7168
	ds_read_b64_tr_b16 v[224:225],v101 offset:7680
	s_waitcnt lgkmcnt(0)
	v_mfma_f32_32x32x16_bf16 v[48:63], v[80:83], v[102:105], v[48:63]
	v_mfma_f32_32x32x16_bf16 v[64:79], v[80:83], v[180:183], v[64:79]
	v_mfma_f32_32x32x16_bf16 v[48:63], v[84:87], v[106:109], v[48:63]
	v_mfma_f32_32x32x16_bf16 v[64:79], v[84:87], v[206:209], v[64:79]
	v_mfma_f32_32x32x16_bf16 v[48:63], v[88:91], v[160:163], v[48:63]
	v_mfma_f32_32x32x16_bf16 v[64:79], v[88:91], v[218:221], v[64:79]
	v_mfma_f32_32x32x16_bf16 v[48:63], v[92:95], v[176:179], v[48:63]
	v_mfma_f32_32x32x16_bf16 v[64:79], v[92:95], v[222:225], v[64:79]
	s_branch .LBB0_1100

; __global__ void __launch_bounds__(512) fwd_megakernel(Args a) {
	.amdhsa_kernel _Z14fwd_megakernel4Args
		.amdhsa_group_segment_fixed_size 256
		.amdhsa_private_segment_fixed_size 0
		.amdhsa_kernarg_size 440
		.amdhsa_user_sgpr_count 2
		.amdhsa_user_sgpr_dispatch_ptr 0
		.amdhsa_user_sgpr_queue_ptr 0
		.amdhsa_user_sgpr_kernarg_segment_ptr 1
		.amdhsa_user_sgpr_dispatch_id 0
		.amdhsa_user_sgpr_kernarg_preload_length 0
		.amdhsa_user_sgpr_kernarg_preload_offset 0
		.amdhsa_user_sgpr_private_segment_size 0
		.amdhsa_uses_dynamic_stack 0
		.amdhsa_enable_private_segment 0
		.amdhsa_system_sgpr_workgroup_id_x 1
		.amdhsa_system_sgpr_workgroup_id_y 0
		.amdhsa_system_sgpr_workgroup_id_z 0
		.amdhsa_system_sgpr_workgroup_info 0
		.amdhsa_system_vgpr_workitem_id 2
		.amdhsa_next_free_vgpr 248
		.amdhsa_next_free_sgpr 102
		.amdhsa_accum_offset 248
		.amdhsa_reserve_vcc 1
		.amdhsa_float_round_mode_32 0
		.amdhsa_float_round_mode_16_64 0
		.amdhsa_float_denorm_mode_32 3
		.amdhsa_float_denorm_mode_16_64 3
		.amdhsa_dx10_clamp 1
		.amdhsa_ieee_mode 1
		.amdhsa_fp16_overflow 0
		.amdhsa_tg_split 0
		.amdhsa_exception_fp_ieee_invalid_op 0
		.amdhsa_exception_fp_denorm_src 0
		.amdhsa_exception_fp_ieee_div_zero 0
		.amdhsa_exception_fp_ieee_overflow 0
		.amdhsa_exception_fp_ieee_underflow 0
		.amdhsa_exception_fp_ieee_inexact 0
		.amdhsa_exception_int_div_zero 0
	.end_amdhsa_kernel

; template <class T> __device__ __forceinline__ T* uni_ptr(T* p) { const unsigned long long v = (unsigned long long)(uintptr_t)p;
;     const unsigned lo = __builtin_amdgcn_readfirstlane((unsigned)v), hi = __builtin_amdgcn_readfirstlane((unsigned)(v >> 32));
;     return (T*)(__attribute__((address_space(1))) T*)(uintptr_t)(((unsigned long long)hi << 32) | lo); }
; __device__ __forceinline__ int uni_i(int v) { return __builtin_amdgcn_readfirstlane(v); }
; __device__ __forceinline__ float uni_f(float v) { return __uint_as_float(__builtin_amdgcn_readfirstlane(__float_as_uint(v))); }
; __global__ void __launch_bounds__(512) fwd_megakernel(Args a) {
amdhsa.kernels:
  - .agpr_count:     0
    .args:
      - .offset:         0
        .size:           184
        .value_kind:     by_value
      - .offset:         184
        .size:           4
        .value_kind:     hidden_block_count_x
      - .offset:         188
        .size:           4
        .value_kind:     hidden_block_count_y
      - .offset:         192
        .size:           4
        .value_kind:     hidden_block_count_z
      - .offset:         196
        .size:           2
        .value_kind:     hidden_group_size_x
      - .offset:         198
        .size:           2
        .value_kind:     hidden_group_size_y
      - .offset:         200
        .size:           2
        .value_kind:     hidden_group_size_z
      - .offset:         202
        .size:           2
        .value_kind:     hidden_remainder_x
      - .offset:         204
        .size:           2
        .value_kind:     hidden_remainder_y
      - .offset:         206
        .size:           2
        .value_kind:     hidden_remainder_z
      - .offset:         224
        .size:           8
        .value_kind:     hidden_global_offset_x
      - .offset:         232
        .size:           8
        .value_kind:     hidden_global_offset_y
      - .offset:         240
        .size:           8
        .value_kind:     hidden_global_offset_z
      - .offset:         248
        .size:           2
        .value_kind:     hidden_grid_dims
      - .offset:         272
        .size:           8
        .value_kind:     hidden_multigrid_sync_arg
      - .offset:         304
        .size:           4
        .value_kind:     hidden_dynamic_lds_size
    .group_segment_fixed_size: 256
    .kernarg_segment_align: 8
    .kernarg_segment_size: 440
    .language:       OpenCL C
    .language_version:
      - 2
      - 0
    .max_flat_workgroup_size: 512
    .name:           _Z14fwd_megakernel4Args
    .private_segment_fixed_size: 0
    .sgpr_count:     108
    .sgpr_spill_count: 154
    .symbol:         _Z14fwd_megakernel4Args.kd
    .uniform_work_group_size: 1
    .uses_dynamic_stack: false
    .vgpr_count:     248
    .vgpr_spill_count: 0
    .wavefront_size: 64
